# branch-GEMM epilogue: touch the gate lines of the later row groups while waiting for the first group (one long round trip instead of four)
# speedup vs baseline: 1.0073x; 1.0073x over previous
; __device__ __forceinline__ u32x4 pack8(f32x4 v0, f32x4 v1) { u32x4 w; w.x = cvt_pk_bf16(v0[0], v0[1]); w.y = cvt_pk_bf16(v0[2], v0[3]); w.z = cvt_pk_bf16(v1[0], v1[1]); w.w = cvt_pk_bf16(v1[2], v1[3]); return w; }
; __device__ __forceinline__ f32x4 dq4u8(unsigned w) { return (f32x4){(float)(w & 0xffu), (float)((w >> 8) & 0xffu), (float)((w >> 16) & 0xffu), (float)(w >> 24)}; }
;     __device__ __forceinline__ void operator()(f32x4 (&acc)[2][2][4][2], const Unit& u, int wr, int wc, int fr, int fq) const {
;     ...
;             for (int q = 0; q < 2; ++q) { const int m = 2 * mp2 + q; const size_t row = (size_t)(row0 + ai * HALF + m * 16); const unsigned char* gp = (const unsigned char*)G + row * 3072 + col0;
; #pragma unroll
;                 for (int bj = 0; bj < 2; ++bj) { ga[q][bj] = *(const u32x2q*)(gp + n * 1024 + bj * HALF); gb[q][bj] = *(const u32x2q*)(gp + nn * 1024 + bj * HALF); } }
;             asm volatile("" : "+v"(ga[0][0]), "+v"(ga[0][1]), "+v"(ga[1][0]), "+v"(ga[1][1]), "+v"(gb[0][0]), "+v"(gb[0][1]), "+v"(gb[1][0]), "+v"(gb[1][1]));
; #pragma unroll
;             for (int q = 0; q < 2; ++q) { const int m = 2 * mp2 + q; const size_t row = (size_t)(row0 + ai * HALF + m * 16);
;                 if (n < 2) {
; #pragma unroll
;                     for (int bj = 0; bj < 2; ++bj) { const f32x4 d0 = dq4u8(gb[q][bj].x), d1 = dq4u8(gb[q][bj].y);
;                         const f32x4 r0 = dq4u8(ga[q][bj].x) * (f32x4){__builtin_amdgcn_rcpf(d0[0]), __builtin_amdgcn_rcpf(d0[1]), __builtin_amdgcn_rcpf(d0[2]), __builtin_amdgcn_rcpf(d0[3])};
;                         const f32x4 r1 = dq4u8(ga[q][bj].y) * (f32x4){__builtin_amdgcn_rcpf(d1[0]), __builtin_amdgcn_rcpf(d1[1]), __builtin_amdgcn_rcpf(d1[2]), __builtin_amdgcn_rcpf(d1[3])};
;                         acc[ai][bj][m][0] *= r0; acc[ai][bj][m][1] *= r1; }
;                 } else { bf16_t* mp = MG + row * 1024 + col0;
; #pragma unroll
;                     for (int bj = 0; bj < 2; ++bj) *(u32x4*)(mp + bj * HALF) = pack8(dq4u8(ga[q][bj].x) * (acc[ai][bj][m][0] * (1.0f / 255.0f)), dq4u8(ga[q][bj].y) * (acc[ai][bj][m][1] * (1.0f / 255.0f))); } }
.LBB0_1041:
	s_lshl_b32 s0, s26, 8
	s_ashr_i32 s6, s26, 2
	s_and_b32 s0, s0, 0x300
	s_cmp_gt_i32 s6, 1
	s_cselect_b64 s[28:29], -1, 0
	s_cmp_lt_i32 s6, 2
	v_or_b32_e32 v0, s0, v180
	s_cselect_b64 s[0:1], -1, 0
	s_cmp_lg_u64 s[0:1], 0
	s_addc_u32 s0, s6, 0
	v_lshl_add_u32 v2, s24, 8, v178
	s_lshl_b32 s24, s6, 10
	s_lshl_b32 s26, s0, 10
	v_lshl_add_u64 v[144:145], s[12:13], 0, v[0:1]
	s_ashr_i32 s25, s24, 31
	s_ashr_i32 s27, s26, 31
	v_mad_i64_i32 v[146:147], s[0:1], v2, s56, v[144:145]
	v_lshl_add_u64 v[148:149], v[146:147], 0, s[24:25]
	v_lshl_add_u64 v[146:147], v[146:147], 0, s[26:27]
	v_or_b32_e32 v150, 16, v2
	global_load_dwordx2 v[156:157], v[148:149], off
	global_load_dwordx2 v[170:171], v[146:147], off
	global_load_dwordx2 v[158:159], v[146:147], off offset:128
	global_load_dwordx2 v[176:177], v[148:149], off offset:128
	v_mad_i64_i32 v[146:147], s[0:1], v150, s56, v[144:145]
	v_lshl_add_u64 v[152:153], v[146:147], 0, s[24:25]
	v_lshl_add_u64 v[146:147], v[146:147], 0, s[26:27]
	global_load_dwordx2 v[154:155], v[152:153], off
	global_load_dwordx2 v[148:149], v[146:147], off
	s_nop 0
	global_load_dwordx2 v[146:147], v[146:147], off offset:128
	s_nop 0
	global_load_dwordx2 v[152:153], v[152:153], off offset:128
	v_add_u32_e32 v200, 0x20, v2
	v_mad_i64_i32 v[202:203], s[0:1], v200, s56, v[144:145]
	v_lshl_add_u64 v[204:205], v[202:203], 0, s[24:25]
	v_lshl_add_u64 v[202:203], v[202:203], 0, s[26:27]
	global_load_dwordx2 v[208:209], v[204:205], off
	global_load_dwordx2 v[208:209], v[204:205], off offset:128
	global_load_dwordx2 v[208:209], v[202:203], off
	global_load_dwordx2 v[208:209], v[202:203], off offset:128
	v_add_u32_e32 v200, 0x30, v2
	v_mad_i64_i32 v[202:203], s[0:1], v200, s56, v[144:145]
	v_lshl_add_u64 v[204:205], v[202:203], 0, s[24:25]
	v_lshl_add_u64 v[202:203], v[202:203], 0, s[26:27]
	global_load_dwordx2 v[208:209], v[204:205], off
	global_load_dwordx2 v[208:209], v[204:205], off offset:128
	global_load_dwordx2 v[208:209], v[202:203], off
	global_load_dwordx2 v[208:209], v[202:203], off offset:128
	v_add_u32_e32 v200, 0x80, v2
	v_mad_i64_i32 v[202:203], s[0:1], v200, s56, v[144:145]
	v_lshl_add_u64 v[204:205], v[202:203], 0, s[24:25]
	v_lshl_add_u64 v[202:203], v[202:203], 0, s[26:27]
	global_load_dwordx2 v[208:209], v[204:205], off
	global_load_dwordx2 v[208:209], v[204:205], off offset:128
	global_load_dwordx2 v[208:209], v[202:203], off
	global_load_dwordx2 v[208:209], v[202:203], off offset:128
	v_add_u32_e32 v200, 0x90, v2
	v_mad_i64_i32 v[202:203], s[0:1], v200, s56, v[144:145]
	v_lshl_add_u64 v[204:205], v[202:203], 0, s[24:25]
	v_lshl_add_u64 v[202:203], v[202:203], 0, s[26:27]
	global_load_dwordx2 v[208:209], v[204:205], off
	global_load_dwordx2 v[208:209], v[204:205], off offset:128
	global_load_dwordx2 v[208:209], v[202:203], off
	global_load_dwordx2 v[208:209], v[202:203], off offset:128
	v_add_u32_e32 v200, 0xa0, v2
	v_mad_i64_i32 v[202:203], s[0:1], v200, s56, v[144:145]
	v_lshl_add_u64 v[204:205], v[202:203], 0, s[24:25]
	v_lshl_add_u64 v[202:203], v[202:203], 0, s[26:27]
	global_load_dwordx2 v[208:209], v[204:205], off
	global_load_dwordx2 v[208:209], v[204:205], off offset:128
	global_load_dwordx2 v[208:209], v[202:203], off
	global_load_dwordx2 v[208:209], v[202:203], off offset:128
	v_add_u32_e32 v200, 0xb0, v2
	v_mad_i64_i32 v[202:203], s[0:1], v200, s56, v[144:145]
	v_lshl_add_u64 v[204:205], v[202:203], 0, s[24:25]
	v_lshl_add_u64 v[202:203], v[202:203], 0, s[26:27]
	global_load_dwordx2 v[208:209], v[204:205], off
	global_load_dwordx2 v[208:209], v[204:205], off offset:128
	global_load_dwordx2 v[208:209], v[202:203], off
	global_load_dwordx2 v[208:209], v[202:203], off offset:128
	s_mov_b64 s[6:7], -1
	v_ashrrev_i32_e32 v3, 31, v2
	v_lshlrev_b32_e32 v0, 1, v0
	s_and_b64 vcc, exec, s[28:29]
	s_waitcnt vmcnt(0)
	s_nop 0
	v_cvt_f32_ubyte1_e32 v173, v156
	v_cvt_f32_ubyte0_e32 v172, v156
	v_cvt_f32_ubyte3_e32 v175, v156
	v_cvt_f32_ubyte2_e32 v174, v156
	v_cvt_f32_ubyte1_e32 v169, v157
	v_cvt_f32_ubyte0_e32 v168, v157
	v_cvt_f32_ubyte3_e32 v167, v157
	v_cvt_f32_ubyte2_e32 v166, v157
	v_cvt_f32_ubyte1_e32 v163, v176
	v_cvt_f32_ubyte0_e32 v162, v176
	v_cvt_f32_ubyte3_e32 v165, v176
	v_cvt_f32_ubyte2_e32 v164, v176
	v_cvt_f32_ubyte1_e32 v161, v177
	v_cvt_f32_ubyte0_e32 v160, v177
	v_cvt_f32_ubyte3_e32 v157, v177
	v_cvt_f32_ubyte2_e32 v156, v177
	s_cbranch_vccz .LBB0_1043
	s_mov_b32 s0, 0x3b808081
	v_pk_mul_f32 v[182:183], v[130:131], s[0:1] op_sel_hi:[1,0]
	v_pk_mul_f32 v[184:185], v[128:129], s[0:1] op_sel_hi:[1,0]
	v_lshlrev_b64 v[176:177], 11, v[2:3]
	v_pk_mul_f32 v[186:187], v[182:183], v[174:175]
	v_pk_mul_f32 v[182:183], v[184:185], v[172:173]
	v_pk_mul_f32 v[184:185], v[126:127], s[0:1] op_sel_hi:[1,0]
	v_pk_mul_f32 v[188:189], v[124:125], s[0:1] op_sel_hi:[1,0]
	v_lshl_add_u64 v[176:177], s[10:11], 0, v[176:177]
	v_pk_mul_f32 v[190:191], v[184:185], v[166:167]
	v_pk_mul_f32 v[184:185], v[188:189], v[168:169]
	v_lshl_add_u64 v[176:177], v[176:177], 0, v[0:1]
	v_cvt_pk_bf16_f32 v182, v182, v183
	v_cvt_pk_bf16_f32 v183, v186, v187
	v_cvt_pk_bf16_f32 v184, v184, v185
	v_cvt_pk_bf16_f32 v185, v190, v191
	global_store_dwordx4 v[176:177], v[182:185], off
	v_pk_mul_f32 v[188:189], v[92:93], s[0:1] op_sel_hi:[1,0]
	s_mov_b64 s[6:7], 0
	v_pk_mul_f32 v[182:183], v[98:99], s[0:1] op_sel_hi:[1,0]
	v_pk_mul_f32 v[184:185], v[96:97], s[0:1] op_sel_hi:[1,0]
	v_pk_mul_f32 v[186:187], v[182:183], v[164:165]
	v_pk_mul_f32 v[182:183], v[184:185], v[162:163]
	v_pk_mul_f32 v[184:185], v[94:95], s[0:1] op_sel_hi:[1,0]
	v_cvt_pk_bf16_f32 v182, v182, v183
	v_pk_mul_f32 v[190:191], v[184:185], v[156:157]
	v_pk_mul_f32 v[184:185], v[188:189], v[160:161]
	v_cvt_pk_bf16_f32 v183, v186, v187
	v_cvt_pk_bf16_f32 v184, v184, v185
	v_cvt_pk_bf16_f32 v185, v190, v191
	global_store_dwordx4 v[176:177], v[182:185], off offset:256
